# out-projection row-sum exchange: the buffer_inv after the arrival poll dropped (the exchange slots are read with agent-scope sc1 loads, nothing else is read from other workgroups afterwards)
# speedup vs baseline: 1.0025x; 1.0001x over previous
.LBB0_674:
.LBB0_675:
	s_waitcnt vmcnt(0) lgkmcnt(0)
	s_barrier
	s_and_saveexec_b64 s[8:9], s[4:5]
	s_cbranch_execz .LBB0_677
	v_lshlrev_b64 v[0:1], 5, v[0:1]
	v_lshl_add_u64 v[0:1], s[6:7], 0, v[0:1]
	global_load_dword v3, v[0:1], off sc1
	global_load_dword v4, v[0:1], off offset:4 sc1
	global_load_dword v5, v[0:1], off offset:8 sc1
	global_load_dword v6, v[0:1], off offset:12 sc1
	global_load_dword v7, v[0:1], off offset:16 sc1
	global_load_dword v8, v[0:1], off offset:20 sc1
	global_load_dword v9, v[0:1], off offset:24 sc1
	s_nop 0
	global_load_dword v0, v[0:1], off offset:28 sc1
	v_mov_b32_e32 v1, 0x358637bd
	s_mov_b32 s3, 0x800000
	s_waitcnt vmcnt(7)
	v_add_f32_e32 v3, 0, v3
	s_waitcnt vmcnt(6)
	v_add_f32_e32 v3, v3, v4
	s_waitcnt vmcnt(5)
	v_add_f32_e32 v3, v3, v5
	s_waitcnt vmcnt(4)
	v_add_f32_e32 v3, v3, v6
	s_waitcnt vmcnt(3)
	v_add_f32_e32 v3, v3, v7
	s_waitcnt vmcnt(2)
	v_add_f32_e32 v3, v3, v8
	s_waitcnt vmcnt(1)
	v_add_f32_e32 v3, v3, v9
	s_waitcnt vmcnt(0)
	v_add_f32_e32 v0, v3, v0
	v_fmac_f32_e32 v1, 0x3a000000, v0
	v_mul_f32_e32 v0, 0x4b800000, v1
	v_cmp_gt_f32_e32 vcc, s3, v1
	s_nop 1
	v_cndmask_b32_e32 v0, v1, v0, vcc
	v_rsq_f32_e32 v0, v0
	s_nop 0
	v_mul_f32_e32 v1, 0x45800000, v0
	v_cndmask_b32_e32 v0, v0, v1, vcc
	v_lshl_add_u32 v1, v2, 2, 0
	ds_write_b32 v1, v0 offset:4096
